# RWKV scan: identity-row waves run at s_setprio 1 inside their step loop
# speedup vs baseline: 1.0012x; 1.0012x over previous
; __device__ __forceinline__ int tidx() { int t = threadIdx.x; asm volatile("" : "+v"(t)); return t; }
; __device__ __forceinline__ float bf2f(unsigned short b) { return __uint_as_float((unsigned)b << 16); }
; __device__ __forceinline__ f2 pfma(f2 a, f2 b, f2 c) { return __builtin_elementwise_fma(a, b, c); }
; template <bool ID> __device__ __forceinline__ void rwkv_scan(const bf16_t* __restrict__ R, const bf16_t* __restrict__ EW, const bf16_t* __restrict__ K, const bf16_t* __restrict__ V, ...
;     unsigned short q1[6], q2[6];
;     { unsigned o = base; q1[0] = R[o]; q1[1] = EW[o]; q1[2] = K[o]; q1[3] = V[o]; q1[4] = A[o]; q1[5] = B[o];
;       o = base + 512u; q2[0] = R[o]; q2[1] = EW[o]; q2[2] = K[o]; q2[3] = V[o]; q2[4] = A[o]; q2[5] = B[o]; }
;     const LAS f32x4* pa = (const LAS f32x4*)L;
;     float sav, sai;
;     { L[lane] = bf2f(q1[4]);
;       f2 av = {0.f, 0.f}, ai = {0.f, 0.f};
; #pragma unroll
;       for (int q = 0; q < 16; ++q) { const f32x4 a4 = pa[q]; const f2 a01 = {a4[0], a4[1]}, a23 = {a4[2], a4[3]};
;           av = pfma(Sv[2 * q], a01, av); av = pfma(Sv[2 * q + 1], a23, av); if (ID) { ai = pfma(Si[2 * q], a01, ai); ai = pfma(Si[2 * q + 1], a23, ai); } }
;       sav = av[0] + av[1]; sai = ai[0] + ai[1]; }
; __device__ void phase_rwkv_scan(const Ctx& p, int l, LAS unsigned char* lds) {
;     ...
;             f2 Sv[32], Si[32]; const int li = tidx() & 63;
; #pragma unroll
;             for (int i = 0; i < 32; ++i) { Sv[i] = (f2){0.f, 0.f}; Si[i] = (f2){(2 * i == li) ? 1.f : 0.f, (2 * i + 1 == li) ? 1.f : 0.f}; }
.Lscan_i:
	v_lshrrev_b32_e32 v78, 5, v139
	v_and_b32_e32 v79, 31, v139
	s_mov_b32 s26, -1
	s_mov_b32 s27, 0
	s_lshl_b32 s14, s36, 13
	s_and_b32 s14, s14, 0xffff0000
	s_lshl_b32 s15, s36, 6
	s_and_b32 s15, s15, 0x1c0
	s_or_b32 s14, s14, s15
	v_add_lshl_u32 v72, s14, v139, 1
	v_add_lshl_u32 v81, s14, v79, 1
	v_mov_b32_e32 v74, s20
	v_mov_b32_e32 v75, s21
	v_add_co_u32_e32 v74, vcc, v74, v81
	s_nop 1
	v_addc_co_u32_e32 v75, vcc, 0, v75, vcc
	v_lshl_add_u32 v76, v78, 4, s10
	v_lshl_add_u32 v77, v139, 2, s10
	v_lshl_add_u32 v251, v79, 2, s10
	v_mov_b32_e32 v246, 1.0
	v_lshlrev_b32_e32 v81, 2, v78
	v_sub_u32_e32 v81, v79, v81
	global_load_ushort v244, v72, s[12:13]
	global_load_ushort v224, v72, s[4:5] offset:0
	global_load_ushort v225, v72, s[0:1] offset:0
	global_load_ushort v226, v72, s[12:13] offset:1024
	global_load_ushort v227, v[74:75], off offset:0
	global_load_ushort v228, v[74:75], off offset:64
	global_load_ushort v230, v72, s[4:5] offset:1024
	global_load_ushort v231, v72, s[0:1] offset:1024
	global_load_ushort v232, v72, s[12:13] offset:2048
	global_load_ushort v233, v[74:75], off offset:1024
	global_load_ushort v234, v[74:75], off offset:1088
	global_load_ushort v82, v72, s[4:5] offset:2048
	global_load_ushort v83, v72, s[0:1] offset:2048
	global_load_ushort v84, v72, s[12:13] offset:3072
	global_load_ushort v85, v[74:75], off offset:2048
	global_load_ushort v86, v[74:75], off offset:2112
	v_add_u32_e32 v72, 0xc00, v72
	v_lshl_add_u64 v[74:75], v[74:75], 0, s[54:55]
	v_lshl_add_u64 v[74:75], v[74:75], 0, s[54:55]
	v_lshl_add_u64 v[74:75], v[74:75], 0, s[54:55]
	global_load_ushort v88, v72, s[4:5] offset:0
	global_load_ushort v89, v72, s[0:1] offset:0
	global_load_ushort v90, v72, s[12:13] offset:1024
	global_load_ushort v91, v[74:75], off offset:0
	global_load_ushort v92, v[74:75], off offset:64
	v_add_u32_e32 v72, 0x400, v72
	v_lshl_add_u64 v[74:75], v[74:75], 0, s[54:55]
	v_mov_b32_e32 v32, 0
	v_mov_b32_e32 v33, 0
	v_mov_b32_e32 v34, 0
	v_mov_b32_e32 v35, 0
	v_mov_b32_e32 v36, 0
	v_mov_b32_e32 v37, 0
	v_mov_b32_e32 v38, 0
	v_mov_b32_e32 v39, 0
	v_mov_b32_e32 v40, 0
	v_mov_b32_e32 v41, 0
	v_mov_b32_e32 v42, 0
	v_mov_b32_e32 v43, 0
	v_mov_b32_e32 v44, 0
	v_mov_b32_e32 v45, 0
	v_mov_b32_e32 v46, 0
	v_mov_b32_e32 v47, 0
	v_mov_b32_e32 v16, 0
	v_mov_b32_e32 v17, 0
	v_mov_b32_e32 v18, 0
	v_mov_b32_e32 v19, 0
	v_mov_b32_e32 v20, 0
	v_mov_b32_e32 v21, 0
	v_mov_b32_e32 v22, 0
	v_mov_b32_e32 v23, 0
	v_mov_b32_e32 v24, 0
	v_mov_b32_e32 v25, 0
	v_mov_b32_e32 v26, 0
	v_mov_b32_e32 v27, 0
	v_mov_b32_e32 v28, 0
	v_mov_b32_e32 v29, 0
	v_mov_b32_e32 v30, 0
	v_mov_b32_e32 v31, 0
	v_cmp_eq_u32_e64 s[14:15], 0, v81
	s_nop 1
	v_cndmask_b32_e64 v0, 0, 1.0, s[14:15]
	v_cndmask_b32_e64 v48, 0, 1.0, s[14:15]
	v_cmp_eq_u32_e64 s[14:15], 1, v81
	s_nop 1
	v_cndmask_b32_e64 v1, 0, 1.0, s[14:15]
	v_cndmask_b32_e64 v49, 0, 1.0, s[14:15]
	v_cmp_eq_u32_e64 s[14:15], 2, v81
	s_nop 1
	v_cndmask_b32_e64 v2, 0, 1.0, s[14:15]
	v_cndmask_b32_e64 v50, 0, 1.0, s[14:15]
	v_cmp_eq_u32_e64 s[14:15], 3, v81
	s_nop 1
	v_cndmask_b32_e64 v3, 0, 1.0, s[14:15]
	v_cndmask_b32_e64 v51, 0, 1.0, s[14:15]
	v_cmp_eq_u32_e64 s[14:15], 8, v81
	s_nop 1
	v_cndmask_b32_e64 v4, 0, 1.0, s[14:15]
	v_cndmask_b32_e64 v52, 0, 1.0, s[14:15]
	v_cmp_eq_u32_e64 s[14:15], 9, v81
	s_nop 1
	v_cndmask_b32_e64 v5, 0, 1.0, s[14:15]
	v_cndmask_b32_e64 v53, 0, 1.0, s[14:15]
	v_cmp_eq_u32_e64 s[14:15], 10, v81
	s_nop 1
	v_cndmask_b32_e64 v6, 0, 1.0, s[14:15]
	v_cndmask_b32_e64 v54, 0, 1.0, s[14:15]
	v_cmp_eq_u32_e64 s[14:15], 11, v81
	s_nop 1
	v_cndmask_b32_e64 v7, 0, 1.0, s[14:15]
	v_cndmask_b32_e64 v55, 0, 1.0, s[14:15]
	v_cmp_eq_u32_e64 s[14:15], 16, v81
	s_nop 1
	v_cndmask_b32_e64 v8, 0, 1.0, s[14:15]
	v_cndmask_b32_e64 v56, 0, 1.0, s[14:15]
	v_cmp_eq_u32_e64 s[14:15], 17, v81
	s_nop 1
	v_cndmask_b32_e64 v9, 0, 1.0, s[14:15]
	v_cndmask_b32_e64 v57, 0, 1.0, s[14:15]
	v_cmp_eq_u32_e64 s[14:15], 18, v81
	s_nop 1
	v_cndmask_b32_e64 v10, 0, 1.0, s[14:15]
	v_cndmask_b32_e64 v58, 0, 1.0, s[14:15]
	v_cmp_eq_u32_e64 s[14:15], 19, v81
	s_nop 1
	v_cndmask_b32_e64 v11, 0, 1.0, s[14:15]
	v_cndmask_b32_e64 v59, 0, 1.0, s[14:15]
	v_cmp_eq_u32_e64 s[14:15], 24, v81
	s_nop 1
	v_cndmask_b32_e64 v12, 0, 1.0, s[14:15]
	v_cndmask_b32_e64 v60, 0, 1.0, s[14:15]
	v_cmp_eq_u32_e64 s[14:15], 25, v81
	s_nop 1
	v_cndmask_b32_e64 v13, 0, 1.0, s[14:15]
	v_cndmask_b32_e64 v61, 0, 1.0, s[14:15]
	v_cmp_eq_u32_e64 s[14:15], 26, v81
	s_nop 1
	v_cndmask_b32_e64 v14, 0, 1.0, s[14:15]
	v_cndmask_b32_e64 v62, 0, 1.0, s[14:15]
	v_cmp_eq_u32_e64 s[14:15], 27, v81
	s_nop 1
	v_cndmask_b32_e64 v15, 0, 1.0, s[14:15]
	v_cndmask_b32_e64 v63, 0, 1.0, s[14:15]
	s_waitcnt vmcnt(15)
	v_lshlrev_b32_e32 v78, 16, v224
	v_mul_f32_e32 v78, 0xbfb8aa3b, v78
	v_exp_f32_e32 v78, v78
	v_lshlrev_b32_e32 v79, 16, v225
	v_lshlrev_b32_e32 v80, 16, v226
	v_mul_f32_e32 v246, v246, v78
	v_mul_f32_e32 v79, v79, v246
	v_mul_f32_e32 v80, v80, v246
	v_rcp_f32_e32 v248, v246
	s_nop 0
	ds_write2st64_b32 v77, v248, v79 offset0:0 offset1:1
	ds_write_b32 v77, v80 offset:512
	ds_read_b32 v249, v251 offset:0
	ds_read_b32 v250, v251 offset:128
	v_lshlrev_b32_e32 v240, 16, v227
	v_lshlrev_b32_e32 v241, 16, v228
	s_waitcnt lgkmcnt(0)
	v_mul_f32_e32 v240, v240, v249
	v_mul_f32_e32 v241, v241, v250
	v_lshlrev_b32_e32 v244, 16, v244
	s_movk_i32 s41, 0
	s_setprio 1

; __device__ __forceinline__ int tidx() { int t = threadIdx.x; asm volatile("" : "+v"(t)); return t; }
; template <bool ID> __device__ __forceinline__ void rwkv_scan(const bf16_t* __restrict__ R, const bf16_t* __restrict__ EW, const bf16_t* __restrict__ K, const bf16_t* __restrict__ V, ...
;     ...
; #pragma unroll 1
;     for (int s = 0; s < nsteps; ++s) {
; __device__ void phase_rwkv_scan(const Ctx& p, int l, LAS unsigned char* lds) {
;     ...
;             const int ln = tidx() & 63; int item2 = item; asm volatile("" : "+s"(item2));
;             float* pp = P + (size_t)item2 * 4096 + ln * 64; float* up = UC + (size_t)item2 * 4096 + ln * 64;
; #pragma unroll
;             for (int i = 0; i < 32; i += 2) { *(float4*)(pp + 2 * i) = make_float4(Si[i][0], Si[i][1], Si[i + 1][0], Si[i + 1][1]); *(float4*)(up + 2 * i) = make_float4(Sv[i][0], Sv[i][1], Sv[i + 1][0], Sv[i + 1][1]); }
.Lscan_i_s3e:
	s_add_i32 s41, s41, 1
	s_cmpk_lg_i32 s41, 32
	s_cbranch_scc1 .Lscan_i_loop
	s_setprio 0
	s_waitcnt vmcnt(0) lgkmcnt(0)
	s_ashr_i32 s15, s36, 31
	s_mov_b32 s14, s36
	s_lshl_b64 s[14:15], s[14:15], 14
	s_add_u32 s14, s37, s14
	s_addc_u32 s15, s38, s15
	v_and_b32_e32 v79, 31, v139
	v_lshrrev_b32_e32 v78, 5, v139
	v_lshlrev_b32_e32 v79, 8, v79
	v_lshl_add_u32 v79, v78, 4, v79
	v_add_u32_e32 v80, 0x2000, v79
	global_store_dwordx4 v79, v[0:3], s[14:15] offset:0
	global_store_dwordx4 v79, v[4:7], s[14:15] offset:32
	global_store_dwordx4 v79, v[8:11], s[14:15] offset:64
	global_store_dwordx4 v79, v[12:15], s[14:15] offset:96
	global_store_dwordx4 v79, v[32:35], s[14:15] offset:128
	global_store_dwordx4 v79, v[36:39], s[14:15] offset:160
	global_store_dwordx4 v79, v[40:43], s[14:15] offset:192
	global_store_dwordx4 v79, v[44:47], s[14:15] offset:224
	global_store_dwordx4 v80, v[16:19], s[14:15] offset:0
	global_store_dwordx4 v80, v[20:23], s[14:15] offset:32
	global_store_dwordx4 v80, v[24:27], s[14:15] offset:64
	global_store_dwordx4 v80, v[28:31], s[14:15] offset:96
	global_store_dwordx4 v80, v[48:51], s[14:15] offset:128
	global_store_dwordx4 v80, v[52:55], s[14:15] offset:160
	global_store_dwordx4 v80, v[56:59], s[14:15] offset:192
	global_store_dwordx4 v80, v[60:63], s[14:15] offset:224
	s_branch .Lscan_tail
